# v25 plus phase-0 weight transpose loops (gate/up, 7 square weights, down) de-serialised: 16 loads in flight per iteration and one wait instead of a full round trip per element
# speedup vs baseline: 1.0169x; 1.0169x over previous
; DI void transpose_item(const float* W, int N, const float* gain, bf16_t* WT, int ldk, int k0, int n0, int drow0, LAS float* scr, int lane) {
; #pragma unroll 8
;     for (int i = 0; i < 32; ++i) { const int kk = 2 * i + (lane >> 5); const float g = gain ? gain[k0 + kk] : 1.f; scr[kk * 33 + (lane & 31)] = W[(size_t)(k0 + kk) * N + n0 + (lane & 31)] * g; }
;     asm volatile("s_waitcnt lgkmcnt(0)" ::: "memory");
.LBB0_31:
	v_mov_b32_e32 v100, 1.0
	v_mov_b32_e32 v101, 1.0
	v_mov_b32_e32 v102, 1.0
	v_mov_b32_e32 v103, 1.0
	v_mov_b32_e32 v104, 1.0
	v_mov_b32_e32 v105, 1.0
	v_mov_b32_e32 v106, 1.0
	v_mov_b32_e32 v107, 1.0
	s_andn2_b64 vcc, exec, s[26:27]
	s_cbranch_vccnz .Ltr_a_ng
	v_lshl_add_u64 v[116:117], s[36:37], 0, v[38:39]
	v_lshl_add_u64 v[118:119], s[36:37], 0, v[24:25]
	global_load_dword v100, v[116:117], off
	global_load_dword v101, v[118:119], off offset:8
	global_load_dword v102, v[118:119], off offset:16
	global_load_dword v103, v[118:119], off offset:24
	global_load_dword v104, v[118:119], off offset:32
	global_load_dword v105, v[118:119], off offset:40
	global_load_dword v106, v[118:119], off offset:48
	global_load_dword v107, v[118:119], off offset:56
.Ltr_a_ng:
	v_lshl_add_u64 v[132:133], v[40:41], 0, s[34:35]
	v_lshl_add_u64 v[134:135], v[36:37], 0, s[34:35]
	v_lshl_add_u64 v[136:137], v[34:35], 0, s[34:35]
	v_lshl_add_u64 v[138:139], v[32:33], 0, s[34:35]
	v_lshl_add_u64 v[140:141], v[30:31], 0, s[34:35]
	v_lshl_add_u64 v[142:143], v[28:29], 0, s[34:35]
	v_lshl_add_u64 v[144:145], v[26:27], 0, s[34:35]
	v_lshl_add_u64 v[146:147], v[22:23], 0, s[34:35]
	global_load_dword v124, v[132:133], off
	global_load_dword v125, v[134:135], off
	global_load_dword v126, v[136:137], off
	global_load_dword v127, v[138:139], off
	global_load_dword v128, v[140:141], off
	global_load_dword v129, v[142:143], off
	global_load_dword v130, v[144:145], off
	global_load_dword v131, v[146:147], off
	s_add_u32 s34, s34, 0x2c000
	s_addc_u32 s35, s35, 0
	s_add_u32 s36, s36, 64
	s_addc_u32 s37, s37, 0
	s_cmp_lg_u32 s34, 0xb0000
	s_waitcnt vmcnt(0)
	v_mul_f32_e32 v100, v100, v124
	ds_write_b32 v6, v100
	v_mul_f32_e32 v101, v101, v125
	ds_write_b32 v6, v101 offset:264
	v_mul_f32_e32 v102, v102, v126
	ds_write_b32 v6, v102 offset:528
	v_mul_f32_e32 v103, v103, v127
	ds_write_b32 v6, v103 offset:792
	v_mul_f32_e32 v104, v104, v128
	ds_write_b32 v6, v104 offset:1056
	v_mul_f32_e32 v105, v105, v129
	ds_write_b32 v6, v105 offset:1320
	v_mul_f32_e32 v106, v106, v130
	ds_write_b32 v6, v106 offset:1584
	v_mul_f32_e32 v107, v107, v131
	ds_write_b32 v6, v107 offset:1848
	v_add_u32_e32 v6, 0x840, v6
	s_cbranch_scc1 .LBB0_31

; DI void transpose_item(const float* W, int N, const float* gain, bf16_t* WT, int ldk, int k0, int n0, int drow0, LAS float* scr, int lane) {
; #pragma unroll 8
;     for (int i = 0; i < 32; ++i) { const int kk = 2 * i + (lane >> 5); const float g = gain ? gain[k0 + kk] : 1.f; scr[kk * 33 + (lane & 31)] = W[(size_t)(k0 + kk) * N + n0 + (lane & 31)] * g; }
;     asm volatile("s_waitcnt lgkmcnt(0)" ::: "memory");
.LBB0_75:
	v_mov_b32_e32 v100, 1.0
	v_mov_b32_e32 v101, 1.0
	v_mov_b32_e32 v102, 1.0
	v_mov_b32_e32 v103, 1.0
	v_mov_b32_e32 v104, 1.0
	v_mov_b32_e32 v105, 1.0
	v_mov_b32_e32 v106, 1.0
	v_mov_b32_e32 v107, 1.0
	s_andn2_b64 vcc, exec, s[38:39]
	s_cbranch_vccnz .Ltr_b_ng
	v_lshl_add_u64 v[116:117], s[34:35], 0, v[6:7]
	v_lshl_add_u64 v[118:119], s[34:35], 0, v[22:23]
	global_load_dword v100, v[116:117], off
	global_load_dword v101, v[118:119], off offset:8
	global_load_dword v102, v[118:119], off offset:16
	global_load_dword v103, v[118:119], off offset:24
	global_load_dword v104, v[118:119], off offset:32
	global_load_dword v105, v[118:119], off offset:40
	global_load_dword v106, v[118:119], off offset:48
	global_load_dword v107, v[118:119], off offset:56
.Ltr_b_ng:
	v_lshl_add_u64 v[132:133], v[38:39], 0, s[36:37]
	v_lshl_add_u64 v[134:135], v[36:37], 0, s[36:37]
	v_lshl_add_u64 v[136:137], v[34:35], 0, s[36:37]
	v_lshl_add_u64 v[138:139], v[32:33], 0, s[36:37]
	v_lshl_add_u64 v[140:141], v[30:31], 0, s[36:37]
	v_lshl_add_u64 v[142:143], v[28:29], 0, s[36:37]
	v_lshl_add_u64 v[144:145], v[26:27], 0, s[36:37]
	v_lshl_add_u64 v[146:147], v[24:25], 0, s[36:37]
	global_load_dword v124, v[132:133], off
	global_load_dword v125, v[134:135], off
	global_load_dword v126, v[136:137], off
	global_load_dword v127, v[138:139], off
	global_load_dword v128, v[140:141], off
	global_load_dword v129, v[142:143], off
	global_load_dword v130, v[144:145], off
	global_load_dword v131, v[146:147], off
	s_add_u32 s36, s36, 0x10000
	s_addc_u32 s37, s37, 0
	s_add_u32 s34, s34, 64
	s_addc_u32 s35, s35, 0
	s_cmp_lg_u32 s36, 0x40000
	s_waitcnt vmcnt(0)
	v_mul_f32_e32 v100, v100, v124
	ds_write_b32 v21, v100
	v_mul_f32_e32 v101, v101, v125
	ds_write_b32 v21, v101 offset:264
	v_mul_f32_e32 v102, v102, v126
	ds_write_b32 v21, v102 offset:528
	v_mul_f32_e32 v103, v103, v127
	ds_write_b32 v21, v103 offset:792
	v_mul_f32_e32 v104, v104, v128
	ds_write_b32 v21, v104 offset:1056
	v_mul_f32_e32 v105, v105, v129
	ds_write_b32 v21, v105 offset:1320
	v_mul_f32_e32 v106, v106, v130
	ds_write_b32 v21, v106 offset:1584
	v_mul_f32_e32 v107, v107, v131
	ds_write_b32 v21, v107 offset:1848
	v_add_u32_e32 v21, 0x840, v21
	s_cbranch_scc1 .LBB0_75

; DI void transpose_item(const float* W, int N, const float* gain, bf16_t* WT, int ldk, int k0, int n0, int drow0, LAS float* scr, int lane) {
; #pragma unroll 8
;     for (int i = 0; i < 32; ++i) { const int kk = 2 * i + (lane >> 5); const float g = gain ? gain[k0 + kk] : 1.f; scr[kk * 33 + (lane & 31)] = W[(size_t)(k0 + kk) * N + n0 + (lane & 31)] * g; }
;     asm volatile("s_waitcnt lgkmcnt(0)" ::: "memory");
.LBB0_96:
	v_mov_b32_e32 v100, 1.0
	v_mov_b32_e32 v101, 1.0
	v_mov_b32_e32 v102, 1.0
	v_mov_b32_e32 v103, 1.0
	v_mov_b32_e32 v104, 1.0
	v_mov_b32_e32 v105, 1.0
	v_mov_b32_e32 v106, 1.0
	v_mov_b32_e32 v107, 1.0
	s_andn2_b64 vcc, exec, s[28:29]
	s_cbranch_vccnz .Ltr_c_ng
	v_lshl_add_u64 v[116:117], s[38:39], 0, v[38:39]
	v_lshl_add_u64 v[118:119], s[38:39], 0, v[24:25]
	global_load_dword v100, v[116:117], off
	global_load_dword v101, v[118:119], off offset:8
	global_load_dword v102, v[118:119], off offset:16
	global_load_dword v103, v[118:119], off offset:24
	global_load_dword v104, v[118:119], off offset:32
	global_load_dword v105, v[118:119], off offset:40
	global_load_dword v106, v[118:119], off offset:48
	global_load_dword v107, v[118:119], off offset:56
.Ltr_c_ng:
	v_lshl_add_u64 v[132:133], v[40:41], 0, s[36:37]
	v_lshl_add_u64 v[134:135], v[36:37], 0, s[36:37]
	v_lshl_add_u64 v[136:137], v[34:35], 0, s[36:37]
	v_lshl_add_u64 v[138:139], v[32:33], 0, s[36:37]
	v_lshl_add_u64 v[140:141], v[30:31], 0, s[36:37]
	v_lshl_add_u64 v[142:143], v[28:29], 0, s[36:37]
	v_lshl_add_u64 v[144:145], v[26:27], 0, s[36:37]
	v_lshl_add_u64 v[146:147], v[22:23], 0, s[36:37]
	global_load_dword v124, v[132:133], off
	global_load_dword v125, v[134:135], off
	global_load_dword v126, v[136:137], off
	global_load_dword v127, v[138:139], off
	global_load_dword v128, v[140:141], off
	global_load_dword v129, v[142:143], off
	global_load_dword v130, v[144:145], off
	global_load_dword v131, v[146:147], off
	s_add_u32 s36, s36, 0x74000
	s_addc_u32 s37, s37, 0
	s_add_u32 s38, s38, 64
	s_addc_u32 s39, s39, 0
	s_cmp_lg_u32 s36, 0x1d0000
	s_waitcnt vmcnt(0)
	v_mul_f32_e32 v100, v100, v124
	ds_write_b32 v6, v100
	v_mul_f32_e32 v101, v101, v125
	ds_write_b32 v6, v101 offset:264
	v_mul_f32_e32 v102, v102, v126
	ds_write_b32 v6, v102 offset:528
	v_mul_f32_e32 v103, v103, v127
	ds_write_b32 v6, v103 offset:792
	v_mul_f32_e32 v104, v104, v128
	ds_write_b32 v6, v104 offset:1056
	v_mul_f32_e32 v105, v105, v129
	ds_write_b32 v6, v105 offset:1320
	v_mul_f32_e32 v106, v106, v130
	ds_write_b32 v6, v106 offset:1584
	v_mul_f32_e32 v107, v107, v131
	ds_write_b32 v6, v107 offset:1848
	v_add_u32_e32 v6, 0x840, v6
	s_cbranch_scc1 .LBB0_96
	s_branch .LBB0_20
